# NSA/DA unit prologues issue tile-0 and tile-1 loads together; grid barrier between OUT(chunk 0) and WIN(chunk 1) skipped (no data dependence)
# speedup vs baseline: 1.0147x; 1.0147x over previous
; #define LAS __attribute__((address_space(3)))
; DI void da_unit(const Params& p, lds8* lds, int bl, int hd, int qb, float lam) {
;     ...
;   bf16_t* QDA = (bf16_t*)(ws + OFF_QDA); const bf16_t* KDA = (const bf16_t*)(ws + OFF_KDA); const bf16_t* VDA = (const bf16_t*)(ws + OFF_VDA);
;   const int r = lane & 31, h = lane >> 5, qs = wid & 3, c = wid >> 2;
;   const size_t rowbase = (size_t)bl * SEQ; const int q0 = qb * 128; const int qpos = q0 + 32 * qs + r;
;   bf16x8 q[4];
;   { const bf16_t* qp = QDA + (rowbase + qpos) * DM + hd * 128 + c * 64 + 8 * h;
; #pragma unroll
;     for (int ks = 0; ks < 4; ++ks) q[ks] = *(const bf16x8*)(qp + 16 * ks); }
;   const int nt = 2 * (qb + 1);
;   DaCtx cx;
;   { const int ch0 = tid, ch1 = tid + 512; cx.sr0 = ch0 >> 4; cx.sc0 = ch0 & 15; cx.sr1 = ch1 >> 4; cx.sc1 = ch1 & 15; }
;   cx.kg = KDA + rowbase * DM + hd * 128; cx.vg = VDA + rowbase * DM + hd * 128;
;   cx.koff = r * DA_KSTR + h * 16 + c * 128;
;   cx.voff = 64 * DA_KSTR + (4 * h + ((lane & 15) >> 2)) * DA_KSTR + ((lane >> 4) & 1) * 32 + (lane & 3) * 8;
;   cx.qpos = qpos; cx.h = h; cx.qs = qs; cx.q0 = q0;
; #pragma unroll
;   for (int t0 = 0; t0 < 2; ++t0) { const size_t ro = (size_t)t0 * 64; lds8* b = lds + t0 * DA_STAGE;
;     const u32x4 kr0 = *(const u32x4*)(cx.kg + (ro + cx.sr0) * DM + cx.sc0 * 8), kr1 = *(const u32x4*)(cx.kg + (ro + cx.sr1) * DM + cx.sc1 * 8);
;     const u32x4 vr0 = *(const u32x4*)(cx.vg + (ro + cx.sr0) * DM + cx.sc0 * 8), vr1 = *(const u32x4*)(cx.vg + (ro + cx.sr1) * DM + cx.sc1 * 8);
;     *(LAS u32x4*)(b + cx.sr0 * DA_KSTR + cx.sc0 * 16) = kr0; *(LAS u32x4*)(b + cx.sr1 * DA_KSTR + cx.sc1 * 16) = kr1;
;     *(LAS u32x4*)(b + 64 * DA_KSTR + cx.sr0 * DA_KSTR + cx.sc0 * 16) = vr0; *(LAS u32x4*)(b + 64 * DA_KSTR + cx.sr1 * DA_KSTR + cx.sc1 * 16) = vr1; }
;   __syncthreads();
.LBB0_845:
	s_or_b64 exec, exec, s[10:11]
	v_mov_b32_e32 v134, v200
	s_ashr_i32 s6, s20, 7
	s_sub_i32 s12, 15, s6
	v_readfirstlane_b32 s16, v134
	s_bfe_u32 s14, s16, 0x20006
	s_lshl_b32 s1, s12, 7
	s_lshl_b32 s3, s14, 5
	s_bfe_u32 s13, s20, 0x40003
	v_and_b32_e32 v179, 31, v134
	s_or_b32 s18, s3, s1
	s_lshl_b32 s0, s13, 11
	v_or_b32_e32 v183, s18, v179
	v_add_u32_e32 v186, s0, v183
	v_readlane_b32 s10, v254, 43
	v_lshlrev_b64 v[0:1], 11, v[186:187]
	v_readlane_b32 s11, v254, 44
	s_ashr_i32 s17, s16, 8
	v_bfe_u32 v135, v134, 5, 1
	v_lshl_add_u64 v[0:1], s[10:11], 0, v[0:1]
	s_lshl_b32 s10, s20, 7
	s_and_b32 s15, s10, 0x380
	s_lshl_b32 s88, s15, 1
	s_lshl_b32 s10, s17, 6
	v_lshl_add_u64 v[0:1], v[0:1], 0, s[88:89]
	s_ashr_i32 s11, s10, 31
	v_lshl_add_u64 v[2:3], s[10:11], 1, v[0:1]
	s_lshl_b32 s10, s13, 22
	v_readlane_b32 s2, v254, 45
	v_lshlrev_b32_e32 v0, 4, v135
	v_mov_b32_e32 v1, v187
	s_add_u32 s11, s2, s10
	v_readlane_b32 s2, v254, 46
	v_lshl_add_u64 v[2:3], v[2:3], 0, v[0:1]
	s_addc_u32 s13, s2, 0
	global_load_dwordx4 v[172:175], v[2:3], off
	global_load_dwordx4 v[168:171], v[2:3], off offset:32
	global_load_dwordx4 v[164:167], v[2:3], off offset:64
	global_load_dwordx4 v[160:163], v[2:3], off offset:96
	s_add_u32 s22, s11, s88
	v_lshlrev_b32_e32 v3, 1, v134
	v_ashrrev_i32_e32 v2, 4, v134
	v_and_b32_e32 v136, 15, v134
	s_addc_u32 s23, s13, 0
	v_readlane_b32 s2, v254, 47
	v_and_b32_e32 v100, 32, v3
	v_lshlrev_b32_e32 v3, 3, v134
	v_add_u32_e32 v1, 0x200, v134
	s_add_u32 s10, s2, s10
	v_readlane_b32 s2, v254, 48
	v_and_b32_e32 v101, 24, v3
	v_ashrrev_i32_e32 v3, 31, v2
	v_lshlrev_b32_e32 v186, 4, v136
	v_ashrrev_i32_e32 v4, 4, v1
	s_addc_u32 s11, s2, 0
	v_lshl_add_u64 v[6:7], s[22:23], 0, v[186:187]
	v_lshlrev_b64 v[96:97], 11, v[2:3]
	s_add_u32 s24, s10, s88
	v_ashrrev_i32_e32 v5, 31, v4
	v_lshl_add_u64 v[8:9], v[6:7], 0, v[96:97]
	s_addc_u32 s25, s11, 0
	global_load_dwordx4 v[10:13], v[8:9], off
	v_lshlrev_b64 v[98:99], 11, v[4:5]
	v_lshl_add_u64 v[22:23], s[24:25], 0, v[186:187]
	s_movk_i32 s2, 0x130
	v_lshl_add_u64 v[6:7], v[6:7], 0, v[98:99]
	v_mul_lo_u32 v138, v4, s2
	global_load_dwordx4 v[14:17], v[6:7], off
	v_lshl_add_u64 v[4:5], v[22:23], 0, v[96:97]
	v_mul_lo_u32 v137, v2, s2
	global_load_dwordx4 v[18:21], v[4:5], off
	v_lshl_add_u64 v[2:3], v[22:23], 0, v[98:99]
	global_load_dwordx4 v[22:25], v[2:3], off
	v_add3_u32 v26, 0, v137, v186
	s_mov_b32 s2, 0x20000
	v_add3_u32 v27, 0, v138, v186
	v_lshlrev_b32_e32 v180, 2, v135
	v_bfe_u32 v1, v134, 2, 2
	s_lshl_b32 s10, s17, 7
	v_or_b32_e32 v1, v180, v1
	v_or_b32_e32 v181, v101, v100
	s_mov_b32 s19, 0
	v_mul_u32_u24_e32 v182, 0x130, v1
	v_add_co_u32_e32 v28, vcc, s2, v8
	s_nop 1
	v_addc_co_u32_e32 v29, vcc, 0, v9, vcc
	v_add_co_u32_e32 v32, vcc, s2, v6
	global_load_dwordx4 v[28:31], v[28:29], off
	s_nop 0
	v_addc_co_u32_e32 v33, vcc, 0, v7, vcc
	v_add_co_u32_e32 v36, vcc, s2, v4
	global_load_dwordx4 v[32:35], v[32:33], off
	s_nop 0
	v_addc_co_u32_e32 v37, vcc, 0, v5, vcc
	v_add_co_u32_e32 v40, vcc, s2, v2
	global_load_dwordx4 v[36:39], v[36:37], off
	s_nop 0
	v_addc_co_u32_e32 v41, vcc, 0, v3, vcc
	global_load_dwordx4 v[40:43], v[40:41], off
	s_cmp_eq_u32 s6, 15
	s_waitcnt vmcnt(7)
	ds_write_b128 v26, v[10:13]
	s_waitcnt vmcnt(6)
	ds_write_b128 v27, v[14:17]
	s_waitcnt vmcnt(5)
	ds_write_b128 v26, v[18:21] offset:19456
	s_waitcnt vmcnt(4)
	ds_write_b128 v27, v[22:25] offset:19456
	s_waitcnt vmcnt(3)
	ds_write_b128 v26, v[28:31] offset:38912
	s_waitcnt vmcnt(2)
	ds_write_b128 v27, v[32:35] offset:38912
	s_waitcnt vmcnt(1)
	ds_write_b128 v26, v[36:39] offset:58368
	s_waitcnt vmcnt(0)
	ds_write_b128 v27, v[40:43] offset:58368
	v_mul_u32_u24_e32 v10, 0x130, v179
	v_add3_u32 v144, v0, v10, s10
	s_mov_b32 s10, 0
	s_waitcnt lgkmcnt(0)
	s_barrier
	s_cbranch_scc1 .LBB0_853
	v_add_co_u32_e32 v0, vcc, 0x40000, v8
	s_mov_b32 s11, 1
	s_nop 0
	v_addc_co_u32_e32 v1, vcc, 0, v9, vcc
	v_add_co_u32_e32 v6, vcc, 0x40000, v6
	s_lshl_b32 s19, s12, 1
	s_nop 0
	v_addc_co_u32_e32 v7, vcc, 0, v7, vcc
	global_load_dwordx4 v[80:83], v[0:1], off
	global_load_dwordx4 v[84:87], v[6:7], off
	v_add_co_u32_e32 v0, vcc, 0x40000, v4
	s_nop 1
	v_addc_co_u32_e32 v1, vcc, 0, v5, vcc
	v_add_co_u32_e32 v2, vcc, 0x40000, v2
	s_nop 1
	v_addc_co_u32_e32 v3, vcc, 0, v3, vcc
	global_load_dwordx4 v[88:91], v[0:1], off
	global_load_dwordx4 v[92:95], v[2:3], off
	v_add_u32_e32 v4, 0, v144
	ds_read_b128 v[0:3], v4
	ds_read_b128 v[32:35], v4 offset:32
	ds_read_b128 v[16:19], v4 offset:9728
	ds_read_b128 v[36:39], v4 offset:9760
	ds_read_b128 v[40:43], v4 offset:64
	ds_read_b128 v[44:47], v4 offset:96
	ds_read_b128 v[48:51], v4 offset:9792
	ds_read_b128 v[52:55], v4 offset:9824
	s_setprio 1
	s_waitcnt lgkmcnt(7)
	v_mfma_f32_32x32x16_bf16 v[0:15], v[0:3], v[172:175], 0
	s_waitcnt lgkmcnt(5)
	v_mfma_f32_32x32x16_bf16 v[16:31], v[16:19], v[172:175], 0
	v_mfma_f32_32x32x16_bf16 v[0:15], v[32:35], v[168:171], v[0:15]
	s_waitcnt lgkmcnt(4)
	v_mfma_f32_32x32x16_bf16 v[16:31], v[36:39], v[168:171], v[16:31]
	s_waitcnt lgkmcnt(3)
	v_mfma_f32_32x32x16_bf16 v[0:15], v[40:43], v[164:167], v[0:15]
	s_waitcnt lgkmcnt(1)
	v_mfma_f32_32x32x16_bf16 v[16:31], v[48:51], v[164:167], v[16:31]
	v_mfma_f32_32x32x16_bf16 v[0:15], v[44:47], v[160:163], v[0:15]
	s_waitcnt lgkmcnt(0)
; DI unsigned cvtpk(float lo, float hi) { f32x2_t v = {lo, hi}; bf16x2_t b = __builtin_convertvector(v, bf16x2_t); return __builtin_bit_cast(unsigned, b); }
; template <int NDVB, bool HAS_NEXT> DI void softmax_def(f32x16& sa0, f32x16& sa1, f32x16& sb0, f32x16& sb1, f32x16 (&O)[NDVB], float& muse, float& l, bool first, bf16x8 (&P)[4], bool check = true) {
;   float mx = 0.f;
;   if (check) mx = rowmax32(sa0, sa1);
;   if (check && (first || __any(mx > 8.f))) {
;     float dl = first ? mx : fmaxf(mx, 0.f);
;     if (mx < -1e29f) dl = 0.f;
;     const float alpha = __builtin_amdgcn_exp2f(-dl);
;     muse += dl; l *= alpha;
; #pragma unroll
;     for (int i = 0; i < 16; ++i) { sa0[i] -= dl; sa1[i] -= dl; }
;     if (HAS_NEXT) {
; #pragma unroll
;       for (int i = 0; i < 16; ++i) { sb0[i] -= dl; sb1[i] -= dl; }
;     }
; #pragma unroll
;     for (int d = 0; d < NDVB; ++d)
; #pragma unroll
;       for (int i = 0; i < 16; ++i) O[d][i] *= alpha;
;   }
;   float sum = 0.f;
; #pragma unroll
;   for (int i = 0; i < 16; ++i) { sa0[i] = __builtin_amdgcn_exp2f(sa0[i]); sum += sa0[i]; }
; #pragma unroll
;   for (int i = 0; i < 16; ++i) { sa1[i] = __builtin_amdgcn_exp2f(sa1[i]); sum += sa1[i]; }
;   l += sum;
;   u32x4 w;
;   w.x = cvtpk(sa0[0], sa0[1]); w.y = cvtpk(sa0[2], sa0[3]); w.z = cvtpk(sa0[4], sa0[5]); w.w = cvtpk(sa0[6], sa0[7]); P[0] = __builtin_bit_cast(bf16x8, w);
;   w.x = cvtpk(sa0[8], sa0[9]); w.y = cvtpk(sa0[10], sa0[11]); w.z = cvtpk(sa0[12], sa0[13]); w.w = cvtpk(sa0[14], sa0[15]); P[1] = __builtin_bit_cast(bf16x8, w);
;   w.x = cvtpk(sa1[0], sa1[1]); w.y = cvtpk(sa1[2], sa1[3]); w.z = cvtpk(sa1[4], sa1[5]); w.w = cvtpk(sa1[6], sa1[7]); P[2] = __builtin_bit_cast(bf16x8, w);
;   w.x = cvtpk(sa1[8], sa1[9]); w.y = cvtpk(sa1[10], sa1[11]); w.z = cvtpk(sa1[12], sa1[13]); w.w = cvtpk(sa1[14], sa1[15]); P[3] = __builtin_bit_cast(bf16x8, w);
	v_mfma_f32_32x32x16_bf16 v[16:31], v[52:55], v[160:163], v[16:31]
	s_setprio 0
	s_nop 8
	v_max_f32_e32 v32, v1, v1
	v_max_f32_e32 v33, v0, v0
	v_max_f32_e32 v32, v33, v32
	v_max3_f32 v33, v2, v3, v17
	v_max3_f32 v32, v32, v16, v18
	v_max3_f32 v32, v32, v19, v4
	v_max3_f32 v33, v33, v6, v7
	v_max3_f32 v32, v32, v5, v20
	v_max3_f32 v33, v33, v22, v23
	v_max3_f32 v32, v32, v21, v8
	v_max3_f32 v33, v33, v10, v11
	v_max3_f32 v32, v32, v9, v24
	v_max3_f32 v33, v33, v26, v27
	v_max3_f32 v32, v32, v25, v12
	v_max3_f32 v33, v33, v14, v15
	v_max3_f32 v32, v32, v13, v28
	v_max3_f32 v33, v33, v30, v31
	v_and_b32_e32 v34, 64, v202
	v_max3_f32 v32, v32, v29, v33
	v_xor_b32_e32 v33, 32, v202
	v_add_u32_e32 v34, 64, v34
	v_cmp_lt_i32_e32 vcc, v33, v34
	v_add3_u32 v212, v181, v182, 0
	s_nop 0
	v_cndmask_b32_e32 v33, v202, v33, vcc
	v_lshlrev_b32_e32 v139, 2, v33
	ds_bpermute_b32 v33, v139, v32
	s_waitcnt lgkmcnt(0)
	v_max_f32_e32 v33, v33, v33
	v_max_f32_e32 v32, v32, v33
	v_cmp_ngt_f32_e32 vcc, s85, v32
	s_nop 1
	v_cndmask_b32_e32 v145, 0, v32, vcc
	v_exp_f32_e64 v32, -v145
	v_sub_f32_e32 v16, v16, v145
	v_sub_f32_e32 v17, v17, v145
	v_sub_f32_e32 v18, v18, v145
	v_sub_f32_e32 v19, v19, v145
	v_mul_f32_e32 v64, 0, v32
	v_exp_f32_e32 v188, v16
	v_exp_f32_e32 v189, v17
	v_exp_f32_e32 v190, v18
	v_exp_f32_e32 v191, v19
	ds_read_b64_tr_b16 v[16:17], v212 offset:19456
	ds_read_b64_tr_b16 v[32:33], v212 offset:19520
	ds_read_b64_tr_b16 v[48:49], v212 offset:19584
	ds_read_b64_tr_b16 v[114:115], v212 offset:19648
	ds_read_b64_tr_b16 v[18:19], v212 offset:21888
	ds_read_b64_tr_b16 v[34:35], v212 offset:21952
	ds_read_b64_tr_b16 v[50:51], v212 offset:22016
	ds_read_b64_tr_b16 v[116:117], v212 offset:22080
	ds_read_b64_tr_b16 v[118:119], v212 offset:24320
	ds_read_b64_tr_b16 v[122:123], v212 offset:24384
	ds_read_b64_tr_b16 v[126:127], v212 offset:24448
	ds_read_b64_tr_b16 v[130:131], v212 offset:24512
	ds_read_b64_tr_b16 v[120:121], v212 offset:26752
	ds_read_b64_tr_b16 v[124:125], v212 offset:26816
	ds_read_b64_tr_b16 v[128:129], v212 offset:26880
	ds_read_b64_tr_b16 v[132:133], v212 offset:26944
	v_sub_f32_e32 v0, v0, v145
	v_sub_f32_e32 v1, v1, v145
	v_sub_f32_e32 v2, v2, v145
	v_sub_f32_e32 v3, v3, v145
	v_sub_f32_e32 v20, v20, v145
	v_sub_f32_e32 v21, v21, v145
	v_sub_f32_e32 v22, v22, v145
	v_sub_f32_e32 v23, v23, v145
	v_sub_f32_e32 v24, v24, v145
	v_sub_f32_e32 v25, v25, v145
	v_sub_f32_e32 v26, v26, v145
	v_sub_f32_e32 v27, v27, v145
	v_sub_f32_e32 v28, v28, v145
	v_sub_f32_e32 v29, v29, v145
	v_sub_f32_e32 v30, v30, v145
	v_sub_f32_e32 v31, v31, v145
	v_sub_f32_e32 v4, v4, v145
	v_sub_f32_e32 v5, v5, v145
	v_sub_f32_e32 v6, v6, v145
	v_sub_f32_e32 v7, v7, v145
	v_sub_f32_e32 v8, v8, v145
	v_sub_f32_e32 v9, v9, v145
	v_sub_f32_e32 v10, v10, v145
	v_sub_f32_e32 v11, v11, v145
	v_sub_f32_e32 v12, v12, v145
	v_sub_f32_e32 v13, v13, v145
	v_sub_f32_e32 v14, v14, v145
	v_sub_f32_e32 v15, v15, v145
	v_exp_f32_e32 v146, v0
	v_exp_f32_e32 v147, v1
	v_exp_f32_e32 v148, v2
	v_exp_f32_e32 v149, v3
	v_exp_f32_e32 v150, v4
	v_exp_f32_e32 v151, v5
	v_exp_f32_e32 v152, v6
	v_exp_f32_e32 v153, v7
	v_exp_f32_e32 v154, v8
	v_exp_f32_e32 v155, v9
	v_exp_f32_e32 v156, v10
	v_exp_f32_e32 v157, v11
	v_exp_f32_e32 v158, v12
	v_exp_f32_e32 v159, v13
	v_exp_f32_e32 v176, v14
	v_exp_f32_e32 v177, v15
	v_exp_f32_e32 v192, v20
	v_exp_f32_e32 v193, v21
	v_exp_f32_e32 v194, v22
	v_exp_f32_e32 v195, v23
	v_exp_f32_e32 v196, v24
	v_exp_f32_e32 v197, v25
	v_exp_f32_e32 v198, v26
	v_exp_f32_e32 v199, v27
	v_exp_f32_e32 v208, v28
	v_exp_f32_e32 v209, v29
	v_exp_f32_e32 v210, v30
	v_exp_f32_e32 v211, v31
	v_mov_b32_e32 v65, v64
	v_mov_b32_e32 v66, v64
	v_mov_b32_e32 v67, v64
	v_mov_b32_e32 v68, v64
	v_mov_b32_e32 v69, v64
	v_mov_b32_e32 v70, v64
	v_mov_b32_e32 v71, v64
	v_mov_b32_e32 v72, v64
	v_mov_b32_e32 v73, v64
	v_mov_b32_e32 v74, v64
	v_mov_b32_e32 v75, v64
	v_mov_b32_e32 v76, v64
	v_mov_b32_e32 v77, v64
	v_mov_b32_e32 v78, v64
	v_mov_b32_e32 v79, v64
	v_cvt_pk_bf16_f32 v140, v146, v147
	v_cvt_pk_bf16_f32 v141, v148, v149
	v_cmp_neq_f32_e32 vcc, 0, v145
	v_cvt_pk_bf16_f32 v102, v196, v197
	v_cvt_pk_bf16_f32 v103, v198, v199
	v_cvt_pk_bf16_f32 v104, v208, v209
	v_cvt_pk_bf16_f32 v105, v210, v211
	v_cvt_pk_bf16_f32 v106, v188, v189
	v_cvt_pk_bf16_f32 v107, v190, v191
	v_cvt_pk_bf16_f32 v108, v192, v193
	v_cvt_pk_bf16_f32 v109, v194, v195
	v_cvt_pk_bf16_f32 v110, v154, v155
	v_cvt_pk_bf16_f32 v111, v156, v157
	v_cvt_pk_bf16_f32 v112, v158, v159
	v_cvt_pk_bf16_f32 v113, v176, v177
	v_cvt_pk_bf16_f32 v142, v150, v151
	v_cvt_pk_bf16_f32 v143, v152, v153
	s_setprio 1
	s_waitcnt lgkmcnt(11)
	v_mfma_f32_32x32x16_bf16 v[0:15], v[16:19], v[140:143], v[64:79]
	s_waitcnt lgkmcnt(10)
	v_mfma_f32_32x32x16_bf16 v[16:31], v[32:35], v[140:143], v[64:79]
	s_waitcnt lgkmcnt(9)
; #define LAS __attribute__((address_space(3)))
; #define MFMA32(a, b, c) __builtin_amdgcn_mfma_f32_32x32x16_bf16((a), (b), (c), 0, 0, 0)
; #define SBAR() __builtin_amdgcn_sched_barrier(0)
; DI s16x4 trrd(const lds8* p) { typedef short v4i16_t __attribute__((ext_vector_type(4))); return __builtin_bit_cast(s16x4, __builtin_amdgcn_ds_read_tr16_b64_v4i16((LAS v4i16_t*)p)); }
; template <int VSTR, int NDVB> DI void pv64(f32x16 (&O)[NDVB], const lds8* vp, const bf16x8 (&P)[4]) {
;   bf16x8 f[2][NDVB];
; #pragma unroll
;   for (int d = 0; d < NDVB; ++d) { const s16x4 lo = trrd(vp + d * 64), hi = trrd(vp + 8 * VSTR + d * 64); f[0][d] = __builtin_shufflevector(lo, hi, 0, 1, 2, 3, 4, 5, 6, 7); }
; #pragma unroll
;   for (int kk = 0; kk < 4; ++kk) {
;     if (kk < 3) {
; #pragma unroll
;       for (int d = 0; d < NDVB; ++d) { const s16x4 lo = trrd(vp + (16 * (kk + 1)) * VSTR + d * 64), hi = trrd(vp + (16 * (kk + 1) + 8) * VSTR + d * 64);
;         f[(kk + 1) & 1][d] = __builtin_shufflevector(lo, hi, 0, 1, 2, 3, 4, 5, 6, 7); }
;     }
;     SBAR();
;     __builtin_amdgcn_s_setprio(1);
; #pragma unroll
;     for (int d = 0; d < NDVB; ++d) O[d] = MFMA32(f[kk & 1][d], P[kk], O[d]);
;     __builtin_amdgcn_s_setprio(0);
;     SBAR();
;   }
; }
; template <bool LOAD2, bool MASK>
; DI void da_step(lds8* lds, const DaCtx& cx, int t, const bf16x8 (&q)[4], f32x16 (&O)[4], float& muse, float& l, f32x16& negm) {
;     ...
;     softmax_def<4, false>(sa0, sa1, du0, du1, O, muse, l, t == 0, P, MASK || (t & 1) == 0);
;     if (__any(muse != mprev)) {
; #pragma unroll
;       for (int i = 0; i < 16; ++i) negm[i] = -muse;
;     }
;     pv64<DA_KSTR, 4>(O, lds + st * DA_STAGE + cx.voff, P);
;   }
;   if (LOAD2) { lds8* b = lds + stn2 * DA_STAGE;
;     *(LAS u32x4*)(b + cx.sr0 * DA_KSTR + cx.sc0 * 16) = kr0; *(LAS u32x4*)(b + cx.sr1 * DA_KSTR + cx.sc1 * 16) = kr1;
;     *(LAS u32x4*)(b + 64 * DA_KSTR + cx.sr0 * DA_KSTR + cx.sc0 * 16) = vr0; *(LAS u32x4*)(b + 64 * DA_KSTR + cx.sr1 * DA_KSTR + cx.sc1 * 16) = vr1;
;     __syncthreads(); }
	v_mfma_f32_32x32x16_bf16 v[32:47], v[48:51], v[140:143], v[64:79]
	v_mov_b64_e32 v[48:49], v[64:65]
	v_mov_b64_e32 v[50:51], v[66:67]
	v_mov_b64_e32 v[52:53], v[68:69]
	v_mov_b64_e32 v[54:55], v[70:71]
	v_mov_b64_e32 v[56:57], v[72:73]
	v_mov_b64_e32 v[58:59], v[74:75]
	v_mov_b64_e32 v[60:61], v[76:77]
	v_mov_b64_e32 v[62:63], v[78:79]
	s_waitcnt lgkmcnt(8)
	s_nop 0
	v_mfma_f32_32x32x16_bf16 v[48:63], v[114:117], v[140:143], v[48:63]
	s_setprio 0
	ds_read_b64_tr_b16 v[66:67], v212 offset:29184
	ds_read_b64_tr_b16 v[70:71], v212 offset:29248
	ds_read_b64_tr_b16 v[74:75], v212 offset:29312
	ds_read_b64_tr_b16 v[114:115], v212 offset:29376
	ds_read_b64_tr_b16 v[68:69], v212 offset:31616
	ds_read_b64_tr_b16 v[72:73], v212 offset:31680
	ds_read_b64_tr_b16 v[76:77], v212 offset:31744
	ds_read_b64_tr_b16 v[116:117], v212 offset:31808
	s_setprio 1
	s_waitcnt lgkmcnt(11)
	v_mfma_f32_32x32x16_bf16 v[0:15], v[118:121], v[110:113], v[0:15]
	s_waitcnt lgkmcnt(10)
	v_mfma_f32_32x32x16_bf16 v[16:31], v[122:125], v[110:113], v[16:31]
	s_waitcnt lgkmcnt(9)
	v_mfma_f32_32x32x16_bf16 v[32:47], v[126:129], v[110:113], v[32:47]
	s_waitcnt lgkmcnt(8)
	v_mfma_f32_32x32x16_bf16 v[48:63], v[130:133], v[110:113], v[48:63]
	s_setprio 0
	ds_read_b64_tr_b16 v[110:111], v212 offset:34048
	ds_read_b64_tr_b16 v[118:119], v212 offset:34112
	ds_read_b64_tr_b16 v[122:123], v212 offset:34176
	ds_read_b64_tr_b16 v[126:127], v212 offset:34240
	ds_read_b64_tr_b16 v[112:113], v212 offset:36480
	ds_read_b64_tr_b16 v[120:121], v212 offset:36544
	ds_read_b64_tr_b16 v[124:125], v212 offset:36608
	ds_read_b64_tr_b16 v[128:129], v212 offset:36672
	s_setprio 1
	s_waitcnt lgkmcnt(11)
	v_mfma_f32_32x32x16_bf16 v[0:15], v[66:69], v[106:109], v[0:15]
	s_waitcnt lgkmcnt(10)
	v_mfma_f32_32x32x16_bf16 v[16:31], v[70:73], v[106:109], v[16:31]
	s_waitcnt lgkmcnt(9)
	v_mfma_f32_32x32x16_bf16 v[32:47], v[74:77], v[106:109], v[32:47]
	s_waitcnt lgkmcnt(8)
	v_mfma_f32_32x32x16_bf16 v[48:63], v[114:117], v[106:109], v[48:63]
	s_setprio 0
	s_setprio 1
	s_waitcnt lgkmcnt(3)
	v_mfma_f32_32x32x16_bf16 v[0:15], v[110:113], v[102:105], v[0:15]
	s_waitcnt lgkmcnt(2)
	v_mfma_f32_32x32x16_bf16 v[16:31], v[118:121], v[102:105], v[16:31]
	s_waitcnt lgkmcnt(1)
	v_mfma_f32_32x32x16_bf16 v[32:47], v[122:125], v[102:105], v[32:47]
	s_waitcnt lgkmcnt(0)
	v_mfma_f32_32x32x16_bf16 v[48:63], v[126:129], v[102:105], v[48:63]
	s_setprio 0
	v_readlane_b32 s2, v255, 5
	v_mov_b32_e32 v67, v187
	s_cmp_lg_u64 vcc, 0
	v_add3_u32 v65, s2, v137, v186
	s_waitcnt vmcnt(3)
	ds_write_b128 v65, v[80:83]
	v_add3_u32 v65, s2, v138, v186
	v_readlane_b32 s2, v255, 6
	s_waitcnt vmcnt(2)
	ds_write_b128 v65, v[84:87]
	s_cselect_b64 s[12:13], -1, 0
	v_add3_u32 v65, s2, v137, v186
	s_waitcnt vmcnt(1)
	ds_write_b128 v65, v[88:91]
	v_add3_u32 v65, s2, v138, v186
	s_waitcnt vmcnt(0)
	ds_write_b128 v65, v[92:95]
	v_add_f32_e32 v65, 0, v146
	v_add_f32_e32 v65, v147, v65
	v_add_f32_e32 v65, v148, v65
	v_add_f32_e32 v65, v149, v65
	v_add_f32_e32 v65, v150, v65
	v_add_f32_e32 v65, v151, v65
	v_add_f32_e32 v65, v152, v65
	v_add_f32_e32 v65, v153, v65
	v_add_f32_e32 v65, v154, v65
	v_add_f32_e32 v65, v155, v65
	v_add_f32_e32 v65, v156, v65
	v_add_f32_e32 v65, v157, v65
	v_add_f32_e32 v65, v158, v65
	v_add_f32_e32 v65, v159, v65
	v_add_f32_e32 v65, v176, v65
	v_add_f32_e32 v65, v177, v65
	v_add_f32_e32 v65, v188, v65
	v_add_f32_e32 v65, v189, v65
	v_add_f32_e32 v65, v190, v65
	v_add_f32_e32 v65, v191, v65
	v_add_f32_e32 v65, v192, v65
	v_add_f32_e32 v65, v193, v65
	v_add_f32_e32 v65, v194, v65
	v_add_f32_e32 v65, v195, v65
	v_add_f32_e32 v65, v196, v65
	v_add_f32_e32 v65, v197, v65
	v_add_f32_e32 v65, v198, v65
	v_add_f32_e32 v65, v199, v65
	v_add_f32_e32 v65, v208, v65
	v_add_f32_e32 v65, v209, v65
	v_add_f32_e32 v65, v210, v65
	v_add_f32_e32 v66, v211, v65
	v_mov_b32_e32 v65, v145
	v_pk_add_f32 v[176:177], v[64:65], v[66:67]
	s_lshl_b32 s6, s6, 1
	v_cndmask_b32_e64 v64, 0, -v177, s[12:13]
	s_lshl_b32 s12, s20, 19
	s_and_b32 s13, s20, 7
	s_sub_i32 s6, 29, s6
	s_and_b32 s12, s12, 0x3c00000
	s_lshl_b32 s13, s13, 8
	s_add_u32 s13, s56, s13
	s_addc_u32 s20, s57, 0
	v_add_u32_e32 v80, v182, v100
	v_readlane_b32 s2, v255, 7
	s_add_u32 s12, s13, s12
	s_addc_u32 s13, s20, 0
	v_add3_u32 v140, v80, v101, s2
	v_readlane_b32 s2, v255, 8
	v_mov_b32_e32 v65, v64
	v_mov_b32_e32 v66, v64
	v_mov_b32_e32 v67, v64
	v_mov_b32_e32 v68, v64
	v_mov_b32_e32 v69, v64
	v_mov_b32_e32 v70, v64
	v_mov_b32_e32 v71, v64
	v_mov_b32_e32 v72, v64
	v_mov_b32_e32 v73, v64
	v_mov_b32_e32 v74, v64
	v_mov_b32_e32 v75, v64
	v_mov_b32_e32 v76, v64
	v_mov_b32_e32 v77, v64
	v_mov_b32_e32 v78, v64
	v_mov_b32_e32 v79, v64
	v_lshl_add_u64 v[130:131], s[12:13], 0, v[96:97]
	v_lshl_add_u64 v[132:133], s[12:13], 0, v[98:99]
	v_add_u32_e32 v141, s2, v144
	s_mov_b32 s12, 0
	s_waitcnt lgkmcnt(0)
	s_barrier

; #define LAS __attribute__((address_space(3)))
; DI float bf2f(unsigned short u) { return __uint_as_float(((unsigned)u) << 16); }
; #define NS_GLOAD(k_, KR, VR) do { const int jj = __builtin_amdgcn_readfirstlane(jl[(k_)]); KR = *(const u32x4*)(kg + (size_t)(64 * jj + sr) * pitch + sc * 8); VR = *(const u32x4*)(vg + (size_t)(64 * jj + sr) * pitch + sc * 8); } while (0)
; #define NS_LSTORE(st_, KR, VR) do { lds8* b = lds + (st_) * NS_STAGE; *(LAS u32x4*)(b + sr * NS_STR + sc * 16) = KR; *(LAS u32x4*)(b + 64 * NS_STR + sr * NS_STR + sc * 16) = VR; } while (0)
; template <int MODE>
; DI void nsa_branch(lds8* lds, const bf16_t* kg, const bf16_t* vg, int pitch, unsigned tiles, const bf16x8 (&q)[4], int qpos, unsigned mybits, int blk,
;                    f32x16 (&O)[2], float& muse, float& l, int tid, int lane, int grp, CmpCap& cap) {
;   const int r = lane & 31, h = lane >> 5;
;   const int sr = tid >> 3, sc = tid & 7;
;   const int koff = r * NS_STR + h * 16;
;   const int voff = 64 * NS_STR + (4 * h + ((lane & 15) >> 2)) * NS_STR + ((lane >> 4) & 1) * 32 + (lane & 3) * 8;
;   volatile LAS int* jl = (volatile LAS int*)(lds + NS_LIST);
;   tiles = __builtin_amdgcn_readfirstlane(tiles);
;   const int ntl = __builtin_popcount(tiles);
;   if (tid < 32) { unsigned below = tiles & ((1u << tid) - 1u); if ((tiles >> tid) & 1u) jl[__builtin_popcount(below)] = tid; }
;   __syncthreads();
; #pragma unroll
;   for (int d = 0; d < 2; ++d)
; #pragma unroll
;     for (int i = 0; i < 16; ++i) O[d][i] = 0.f;
;   muse = 0.f; l = 0.f;
;   u32x4 kra, vra;
;     ...
;   NS_GLOAD(0, kra, vra); NS_LSTORE(0, kra, vra);
;   if (ntl > 1) { NS_GLOAD(1, kra, vra); NS_LSTORE(1, kra, vra); }
;   __syncthreads();
; DI void nsa_unit(const Params& p, lds8* lds, int bl, int g, int qb32) {
;     ...
;   bf16x8 qraw[4], qrot[4];
;   { const bf16_t* qp = QNS + (rowbase + qpos) * DM + hh * 64 + 8 * h;
; #pragma unroll
;     for (int ks = 0; ks < 4; ++ks) qraw[ks] = *(const bf16x8*)(qp + 16 * ks); }
;   const bf16_t* gp = GNS + (rowbase + qpos) * 64 + hh * 3;
;   const float g0 = bf2f(gp[0]), g1 = bf2f(gp[1]), g2 = bf2f(gp[2]);
.LBB0_898:
	v_writelane_b32 v255, s88, 37
	s_movk_i32 s94, 0x84
	s_nop 0
	v_writelane_b32 v255, s89, 38
	s_or_b64 exec, exec, s[8:9]
	s_ashr_i32 s1, s0, 5
	v_mov_b32_e32 v136, v200
	s_sub_i32 s3, 63, s1
	s_bfe_u32 s71, s0, 0x40001
	s_and_b32 s70, s0, 1
	s_lshl_b32 s2, s3, 5
	v_readfirstlane_b32 s0, v136
	s_ashr_i32 s1, s0, 6
	v_and_b32_e32 v52, 31, v136
	s_lshl_b32 s0, s70, 3
	v_writelane_b32 v255, s1, 39
	s_add_i32 s0, s1, s0
	s_lshl_b32 s1, s71, 11
	v_or_b32_e32 v211, s2, v52
	v_add_u32_e32 v186, s1, v211
	v_readlane_b32 s8, v254, 51
	v_lshlrev_b64 v[0:1], 11, v[186:187]
	v_readlane_b32 s9, v254, 52
	s_lshl_b32 s96, s0, 6
	v_bfe_u32 v55, v136, 5, 1
	v_lshl_add_u64 v[0:1], s[8:9], 0, v[0:1]
	s_ashr_i32 s97, s96, 31
	v_lshl_add_u64 v[0:1], s[96:97], 1, v[0:1]
	v_lshlrev_b32_e32 v2, 4, v55
	v_mov_b32_e32 v3, v187
	v_lshl_add_u64 v[0:1], v[0:1], 0, v[2:3]
	v_readlane_b32 s8, v254, 57
	global_load_dwordx4 v[44:47], v[0:1], off
	global_load_dwordx4 v[36:39], v[0:1], off offset:32
	global_load_dwordx4 v[40:43], v[0:1], off offset:64
	global_load_dwordx4 v[32:35], v[0:1], off offset:96
	v_lshlrev_b64 v[0:1], 7, v[186:187]
	v_readlane_b32 s9, v254, 58
	v_writelane_b32 v255, s2, 40
	v_writelane_b32 v255, s1, 41
	v_lshl_add_u64 v[0:1], s[8:9], 0, v[0:1]
	s_mul_i32 s8, s0, 3
	s_ashr_i32 s9, s8, 31
	v_lshl_add_u64 v[0:1], s[8:9], 1, v[0:1]
	global_load_dword v209, v[0:1], off
	global_load_ushort v210, v[0:1], off offset:4
	v_cmp_gt_u32_e32 vcc, 2, v136
	s_and_saveexec_b64 s[8:9], vcc
	v_lshl_add_u32 v0, v136, 2, 0
	v_add_u32_e32 v0, 0x16d10, v0
	ds_write_b32 v0, v136
	s_or_b64 exec, exec, s[8:9]
	s_lshl_b32 s0, s70, 14
	s_lshl_b32 s6, s71, 15
	s_or_b32 s0, s6, s0
	v_readlane_b32 s1, v254, 55
	s_add_u32 s10, s1, s0
	v_readlane_b32 s1, v254, 56
	s_addc_u32 s11, s1, 0
	v_readlane_b32 s1, v254, 61
	v_and_b32_e32 v199, 63, v136
	s_add_u32 s8, s1, s0
	v_readlane_b32 s0, v254, 62
	s_addc_u32 s9, s0, 0
	v_lshlrev_b32_e32 v214, 2, v55
	v_lshrrev_b32_e32 v0, 2, v136
	v_lshlrev_b32_e32 v1, 3, v199
	s_add_i32 s0, 0, 0x16d10
	v_and_or_b32 v51, v0, 3, v214
	v_lshlrev_b32_e32 v0, 1, v199
	v_and_b32_e32 v1, 24, v1
	v_mov_b32_e32 v48, s0
	v_and_or_b32 v66, v0, 32, v1
	s_waitcnt lgkmcnt(0)
	s_barrier
	v_readlane_b32 s2, v255, 9
	ds_read_b32 v0, v48
	v_ashrrev_i32_e32 v212, 3, v136
	v_and_b32_e32 v54, 7, v136
	v_mov_b32_e32 v50, s2
	ds_read_b32 v9, v50
	v_lshlrev_b32_e32 v192, 4, v54
	v_mov_b32_e32 v193, v187
	s_movk_i32 s1, 0x90
	v_mul_lo_u32 v8, v212, s1
	v_mul_u32_u24_e32 v208, 0x90, v52
	v_lshl_add_u32 v213, v55, 4, v208
	s_waitcnt lgkmcnt(0)
	v_readfirstlane_b32 s6, v0
	v_readfirstlane_b32 s77, v9
	v_add3_u32 v215, 0, v8, v192
	s_nop 0
	v_lshl_add_u32 v0, s6, 6, v212
	s_nop 0
	v_lshl_add_u32 v10, s77, 6, v212
	v_ashrrev_i32_e32 v1, 31, v0
	v_ashrrev_i32_e32 v11, 31, v10
	v_lshlrev_b64 v[4:5], 7, v[0:1]
	v_lshlrev_b64 v[12:13], 7, v[10:11]
	v_lshl_add_u64 v[0:1], s[10:11], 0, v[4:5]
	v_lshl_add_u64 v[0:1], v[0:1], 0, v[192:193]
	v_lshl_add_u64 v[4:5], s[8:9], 0, v[4:5]
	global_load_dwordx4 v[0:3], v[0:1], off
	v_lshl_add_u64 v[4:5], v[4:5], 0, v[192:193]
	global_load_dwordx4 v[4:7], v[4:5], off
	v_lshl_add_u64 v[8:9], s[10:11], 0, v[12:13]
	v_lshl_add_u64 v[8:9], v[8:9], 0, v[192:193]
	v_lshl_add_u64 v[12:13], s[8:9], 0, v[12:13]
	global_load_dwordx4 v[8:11], v[8:9], off
	v_lshl_add_u64 v[12:13], v[12:13], 0, v[192:193]
	global_load_dwordx4 v[12:15], v[12:13], off
	s_waitcnt vmcnt(3)
	ds_write_b128 v215, v[0:3]
	s_waitcnt vmcnt(2)
	ds_write_b128 v215, v[4:7] offset:9216
	s_waitcnt vmcnt(1)
	ds_write_b128 v215, v[8:11] offset:18432
	s_waitcnt vmcnt(0)
	ds_write_b128 v215, v[12:15] offset:27648
	v_subrev_u32_e32 v0, 31, v211
	v_and_b32_e32 v1, 64, v202
	v_ashrrev_i32_e32 v121, 4, v0
	v_xor_b32_e32 v0, 32, v202
	v_add_u32_e32 v53, 64, v1
	v_cmp_lt_i32_e32 vcc, v0, v53
	s_waitcnt lgkmcnt(0)
	s_barrier
	v_cndmask_b32_e32 v0, v202, v0, vcc
	v_lshlrev_b32_e32 v193, 2, v0
	v_add_u32_e32 v134, 0, v213
	ds_read_b128 v[56:59], v134
	ds_read_b128 v[60:63], v134 offset:32
	ds_read_b128 v[68:71], v134 offset:4608
	ds_read_b128 v[72:75], v134 offset:4640
	ds_read_b128 v[76:79], v134 offset:64
	ds_read_b128 v[80:83], v134 offset:96
	ds_read_b128 v[84:87], v134 offset:4672
	ds_read_b128 v[88:91], v134 offset:4704
	s_setprio 1
	s_mov_b32 s77, s76
	s_mov_b32 s78, s76
	s_mov_b32 s79, s76
	s_mov_b32 s80, s76
	s_mov_b32 s81, s76
	s_mov_b32 s82, s76
	s_mov_b32 s83, s76
	s_mov_b32 s84, s76
	s_mov_b32 s85, s76
	s_mov_b32 s86, s76
	s_mov_b32 s87, s76
	s_mov_b32 s88, s76
	s_mov_b32 s89, s76
	s_mov_b32 s90, s76
	s_mov_b32 s91, s76
	v_mov_b64_e32 v[0:1], s[76:77]
	v_mov_b64_e32 v[2:3], s[78:79]
	v_mov_b64_e32 v[4:5], s[80:81]
	v_mov_b64_e32 v[6:7], s[82:83]
	v_mov_b64_e32 v[8:9], s[84:85]
	v_mov_b64_e32 v[10:11], s[86:87]
	v_mov_b64_e32 v[12:13], s[88:89]
	v_mov_b64_e32 v[14:15], s[90:91]
	s_waitcnt lgkmcnt(7)
	s_nop 0
	v_mfma_f32_32x32x16_bf16 v[16:31], v[56:59], v[44:47], v[0:15]
	s_waitcnt lgkmcnt(5)
	v_mfma_f32_32x32x16_bf16 v[0:15], v[68:71], v[44:47], v[0:15]
	v_mfma_f32_32x32x16_bf16 v[16:31], v[60:63], v[36:39], v[16:31]
	s_waitcnt lgkmcnt(4)
	v_mfma_f32_32x32x16_bf16 v[0:15], v[72:75], v[36:39], v[0:15]
	s_waitcnt lgkmcnt(3)
	v_mfma_f32_32x32x16_bf16 v[16:31], v[76:79], v[40:43], v[16:31]
	s_waitcnt lgkmcnt(1)
	v_mfma_f32_32x32x16_bf16 v[0:15], v[84:87], v[40:43], v[0:15]
	v_mfma_f32_32x32x16_bf16 v[16:31], v[80:83], v[32:35], v[16:31]
	s_waitcnt lgkmcnt(0)
	v_mfma_f32_32x32x16_bf16 v[0:15], v[88:91], v[32:35], v[0:15]
	s_setprio 0
	ds_read_b32 v48, v48
	s_mov_b32 s85, 0xefa18f08
	v_mad_u32_u24 v216, v51, s1, v66
	v_add_u32_e32 v96, 0, v216
	s_waitcnt lgkmcnt(0)
; #define LAS __attribute__((address_space(3)))
; DI float rowmax32(const f32x16& s0, const f32x16& s1) {
;   float a = fmaxf(fmaxf(s0[0], s0[1]), s1[0]), b = fmaxf(fmaxf(s0[2], s0[3]), s1[1]); a = fmaxf(fmaxf(a, s1[2]), s1[3]);
; #pragma unroll
;   for (int r = 4; r < 16; r += 4) { a = fmaxf(fmaxf(a, s0[r]), s0[r + 1]); b = fmaxf(fmaxf(b, s0[r + 2]), s0[r + 3]); a = fmaxf(fmaxf(a, s1[r]), s1[r + 1]); b = fmaxf(fmaxf(b, s1[r + 2]), s1[r + 3]); }
;   const float m = fmaxf(a, b);
;   return fmaxf(m, __shfl_xor(m, 32));
; }
; template <int MODE, int SLOT> DI void ns_valu(volatile LAS int* jl, int t, int ntl, int qpos, int h, int blk, f32x16& s0, f32x16& s1, f32x16& du0, f32x16& du1, f32x16 (&O)[2], float& muse, float& l, bf16x8 (&P)[4], CmpCap& cap) {
;     if (t < ntl) {
;       const int j = __builtin_amdgcn_readfirstlane(jl[t]);
;       if (MODE == 0) {
;         const int lim = ((qpos - 31) >> 4) - 64 * j - 4 * h;
; #pragma unroll
;         for (int i = 0; i < 16; ++i) { const int ci = (i & 3) + 8 * (i >> 2); if (ci > lim) s0[i] = NEG; if (ci + 32 > lim) s1[i] = NEG; }
	v_readfirstlane_b32 s6, v48
	s_nop 1
	v_lshl_or_b32 v48, s6, 6, v214
	v_sub_u32_e32 v48, v121, v48
	v_cmp_gt_i32_e64 s[64:65], 26, v48
	v_cmp_gt_i32_e64 s[68:69], 27, v48
	v_cmp_gt_i32_e64 s[60:61], 25, v48
	s_and_b64 s[64:65], s[68:69], s[64:65]
	v_cmp_gt_i32_e64 s[56:57], 24, v48
	s_and_b64 s[60:61], s[64:65], s[60:61]
	v_cmp_gt_i32_e64 s[52:53], 19, v48
	s_and_b64 s[56:57], s[60:61], s[56:57]
	v_cmp_gt_i32_e64 s[48:49], 18, v48
	s_and_b64 s[52:53], s[56:57], s[52:53]
	v_cmp_gt_i32_e64 s[44:45], 17, v48
	s_and_b64 s[48:49], s[52:53], s[48:49]
	v_cmp_gt_i32_e64 s[40:41], 16, v48
	s_and_b64 s[44:45], s[48:49], s[44:45]
	v_cmp_gt_i32_e64 s[36:37], 11, v48
	s_and_b64 s[40:41], s[44:45], s[40:41]
	v_cmp_gt_i32_e64 s[30:31], 10, v48
	s_and_b64 s[36:37], s[40:41], s[36:37]
	v_cmp_gt_i32_e64 s[26:27], 9, v48
	s_and_b64 s[30:31], s[36:37], s[30:31]
	v_cmp_gt_i32_e64 s[22:23], 8, v48
	s_and_b64 s[26:27], s[30:31], s[26:27]
	v_cmp_gt_i32_e64 s[20:21], 3, v48
	s_and_b64 s[22:23], s[26:27], s[22:23]
	v_cmp_gt_i32_e64 s[18:19], 2, v48
	s_and_b64 s[20:21], s[22:23], s[20:21]
	v_cmp_gt_i32_e64 s[16:17], 1, v48
	s_and_b64 s[18:19], s[20:21], s[18:19]
	v_cmp_gt_i32_e64 s[14:15], 0, v48
	s_and_b64 s[16:17], s[18:19], s[16:17]
	s_and_b64 s[14:15], s[16:17], s[14:15]
	v_cmp_gt_i32_e64 s[66:67], 58, v48
	v_cndmask_b32_e64 v16, v16, v207, s[14:15]
	v_cmp_gt_i32_e64 s[14:15], 59, v48
	v_cmp_gt_i32_e64 s[62:63], 57, v48
	v_cmp_gt_i32_e64 s[58:59], 56, v48
	v_cndmask_b32_e64 v15, v15, v207, s[14:15]
	s_and_b64 s[14:15], s[14:15], s[66:67]
	v_cndmask_b32_e64 v14, v14, v207, s[14:15]
	s_and_b64 s[14:15], s[14:15], s[62:63]
	v_cmp_gt_i32_e64 s[54:55], 51, v48
	v_cndmask_b32_e64 v13, v13, v207, s[14:15]
	s_and_b64 s[14:15], s[14:15], s[58:59]
	v_cmp_gt_i32_e64 s[50:51], 50, v48
	v_cndmask_b32_e64 v12, v12, v207, s[14:15]
	s_and_b64 s[14:15], s[14:15], s[54:55]
	v_cmp_gt_i32_e64 s[46:47], 49, v48
	v_cndmask_b32_e64 v11, v11, v207, s[14:15]
	s_and_b64 s[14:15], s[14:15], s[50:51]
	v_cmp_gt_i32_e64 s[42:43], 48, v48
	v_cndmask_b32_e64 v10, v10, v207, s[14:15]
	s_and_b64 s[14:15], s[14:15], s[46:47]
	v_cmp_gt_i32_e64 s[38:39], 43, v48
	v_cndmask_b32_e64 v9, v9, v207, s[14:15]
	s_and_b64 s[14:15], s[14:15], s[42:43]
	v_cmp_gt_i32_e64 s[34:35], 42, v48
	v_cndmask_b32_e64 v8, v8, v207, s[14:15]
	s_and_b64 s[14:15], s[14:15], s[38:39]
	v_cmp_gt_i32_e64 s[28:29], 41, v48
	v_cndmask_b32_e64 v7, v7, v207, s[14:15]
	s_and_b64 s[14:15], s[14:15], s[34:35]
	v_cmp_gt_i32_e64 s[24:25], 40, v48
	v_cndmask_b32_e64 v6, v6, v207, s[14:15]
	s_and_b64 s[14:15], s[14:15], s[28:29]
	v_cmp_gt_i32_e64 s[12:13], 35, v48
	v_cndmask_b32_e64 v5, v5, v207, s[14:15]
	s_and_b64 s[14:15], s[14:15], s[24:25]
	v_cmp_gt_i32_e64 s[10:11], 34, v48
	s_and_b64 s[12:13], s[14:15], s[12:13]
	v_cmp_gt_i32_e64 s[8:9], 33, v48
	s_and_b64 s[10:11], s[12:13], s[10:11]
	v_cmp_gt_i32_e32 vcc, 32, v48
	v_cndmask_b32_e64 v17, v17, v207, s[16:17]
	s_and_b64 s[8:9], s[10:11], s[8:9]
	s_and_b64 vcc, s[8:9], vcc
	v_max_f32_e32 v48, v17, v17
	v_max_f32_e32 v49, v16, v16
	v_cndmask_b32_e64 v19, v19, v207, s[20:21]
	v_cndmask_b32_e64 v18, v18, v207, s[18:19]
	v_cndmask_b32_e64 v2, v2, v207, s[10:11]
	v_cndmask_b32_e64 v1, v1, v207, s[8:9]
	v_cndmask_b32_e32 v0, v0, v207, vcc
	v_max_f32_e32 v48, v49, v48
	v_cndmask_b32_e64 v23, v23, v207, s[36:37]
	v_cndmask_b32_e64 v22, v22, v207, s[30:31]
	v_cndmask_b32_e64 v20, v20, v207, s[22:23]
	v_cndmask_b32_e64 v3, v3, v207, s[12:13]
	v_max3_f32 v49, v18, v19, v1
	v_max3_f32 v48, v48, v0, v2
	v_cndmask_b32_e64 v21, v21, v207, s[26:27]
	v_cndmask_b32_e64 v4, v4, v207, s[14:15]
	v_max3_f32 v48, v48, v3, v20
	v_max3_f32 v49, v49, v22, v23
	v_cndmask_b32_e64 v27, v27, v207, s[52:53]
	v_cndmask_b32_e64 v26, v26, v207, s[48:49]
	v_cndmask_b32_e64 v24, v24, v207, s[40:41]
	v_max3_f32 v48, v48, v21, v4
	v_max3_f32 v49, v49, v6, v7
	v_cndmask_b32_e64 v25, v25, v207, s[44:45]
	v_max3_f32 v48, v48, v5, v24
	v_max3_f32 v49, v49, v26, v27
	v_cndmask_b32_e64 v31, v31, v207, s[68:69]
	v_cndmask_b32_e64 v30, v30, v207, s[64:65]
	v_cndmask_b32_e64 v28, v28, v207, s[56:57]
	v_max3_f32 v48, v48, v25, v8
	v_max3_f32 v49, v49, v10, v11
	v_cndmask_b32_e64 v29, v29, v207, s[60:61]
	v_max3_f32 v48, v48, v9, v28
	v_max3_f32 v49, v49, v30, v31
	v_max3_f32 v48, v48, v29, v12
	v_max3_f32 v49, v49, v14, v15
	v_max3_f32 v48, v48, v13, v49
	ds_bpermute_b32 v49, v193, v48
	s_waitcnt lgkmcnt(0)
; template <int VSTR, int NDVB> DI void pv64(f32x16 (&O)[NDVB], const lds8* vp, const bf16x8 (&P)[4]) {
;   bf16x8 f[2][NDVB];
; #pragma unroll
;   for (int d = 0; d < NDVB; ++d) { const s16x4 lo = trrd(vp + d * 64), hi = trrd(vp + 8 * VSTR + d * 64); f[0][d] = __builtin_shufflevector(lo, hi, 0, 1, 2, 3, 4, 5, 6, 7); }
; #pragma unroll
;   for (int kk = 0; kk < 4; ++kk) {
;     if (kk < 3) {
; #pragma unroll
;       for (int d = 0; d < NDVB; ++d) { const s16x4 lo = trrd(vp + (16 * (kk + 1)) * VSTR + d * 64), hi = trrd(vp + (16 * (kk + 1) + 8) * VSTR + d * 64);
;         f[(kk + 1) & 1][d] = __builtin_shufflevector(lo, hi, 0, 1, 2, 3, 4, 5, 6, 7); }
;     }
;     SBAR();
; template <int NDVB, bool HAS_NEXT> DI void softmax_def(f32x16& sa0, f32x16& sa1, f32x16& sb0, f32x16& sb1, f32x16 (&O)[NDVB], float& muse, float& l, bool first, bf16x8 (&P)[4], bool check = true) {
;   float mx = 0.f;
;   if (check) mx = rowmax32(sa0, sa1);
;   if (check && (first || __any(mx > 8.f))) {
;     float dl = first ? mx : fmaxf(mx, 0.f);
;     if (mx < -1e29f) dl = 0.f;
;     const float alpha = __builtin_amdgcn_exp2f(-dl);
;     muse += dl; l *= alpha;
; #pragma unroll
;     for (int i = 0; i < 16; ++i) { sa0[i] -= dl; sa1[i] -= dl; }
;     if (HAS_NEXT) {
; #pragma unroll
;       for (int i = 0; i < 16; ++i) { sb0[i] -= dl; sb1[i] -= dl; }
;     }
; #pragma unroll
;     for (int d = 0; d < NDVB; ++d)
; #pragma unroll
;       for (int i = 0; i < 16; ++i) O[d][i] *= alpha;
;   }
;   float sum = 0.f;
; #pragma unroll
;   for (int i = 0; i < 16; ++i) { sa0[i] = __builtin_amdgcn_exp2f(sa0[i]); sum += sa0[i]; }
; #pragma unroll
;   for (int i = 0; i < 16; ++i) { sa1[i] = __builtin_amdgcn_exp2f(sa1[i]); sum += sa1[i]; }
;   l += sum;
;   u32x4 w;
;   w.x = cvtpk(sa0[0], sa0[1]); w.y = cvtpk(sa0[2], sa0[3]); w.z = cvtpk(sa0[4], sa0[5]); w.w = cvtpk(sa0[6], sa0[7]); P[0] = __builtin_bit_cast(bf16x8, w);
;   w.x = cvtpk(sa0[8], sa0[9]); w.y = cvtpk(sa0[10], sa0[11]); w.z = cvtpk(sa0[12], sa0[13]); w.w = cvtpk(sa0[14], sa0[15]); P[1] = __builtin_bit_cast(bf16x8, w);
;   w.x = cvtpk(sa1[0], sa1[1]); w.y = cvtpk(sa1[2], sa1[3]); w.z = cvtpk(sa1[4], sa1[5]); w.w = cvtpk(sa1[6], sa1[7]); P[2] = __builtin_bit_cast(bf16x8, w);
;   w.x = cvtpk(sa1[8], sa1[9]); w.y = cvtpk(sa1[10], sa1[11]); w.z = cvtpk(sa1[12], sa1[13]); w.w = cvtpk(sa1[14], sa1[15]); P[3] = __builtin_bit_cast(bf16x8, w);
	v_max_f32_e32 v49, v49, v49
	v_max_f32_e32 v48, v48, v49
	v_cmp_ngt_f32_e32 vcc, s85, v48
	s_nop 1
	v_cndmask_b32_e32 v65, 0, v48, vcc
	v_sub_f32_e32 v16, v16, v65
	v_sub_f32_e32 v17, v17, v65
	v_exp_f32_e32 v97, v16
	v_sub_f32_e32 v18, v18, v65
	v_exp_f32_e32 v98, v17
	v_sub_f32_e32 v19, v19, v65
	v_exp_f32_e32 v99, v18
	v_sub_f32_e32 v20, v20, v65
	v_exp_f32_e32 v56, v19
	v_sub_f32_e32 v21, v21, v65
	v_add_f32_e32 v16, 0, v97
	v_exp_f32_e32 v100, v20
	v_sub_f32_e32 v22, v22, v65
	v_add_f32_e32 v16, v98, v16
	v_exp_f32_e32 v101, v21
	v_sub_f32_e32 v23, v23, v65
	v_add_f32_e32 v16, v99, v16
	v_exp_f32_e32 v102, v22
	v_sub_f32_e32 v24, v24, v65
	v_add_f32_e32 v16, v56, v16
	v_exp_f32_e32 v57, v23
	v_sub_f32_e32 v25, v25, v65
	v_add_f32_e32 v16, v100, v16
	v_exp_f32_e32 v103, v24
	v_sub_f32_e32 v26, v26, v65
	v_add_f32_e32 v16, v101, v16
	v_exp_f32_e32 v104, v25
	v_sub_f32_e32 v27, v27, v65
	v_add_f32_e32 v16, v102, v16
	v_exp_f32_e32 v105, v26
	v_sub_f32_e32 v28, v28, v65
	v_add_f32_e32 v16, v57, v16
	v_exp_f32_e32 v58, v27
	v_sub_f32_e32 v29, v29, v65
	v_add_f32_e32 v16, v103, v16
	v_exp_f32_e32 v106, v28
	v_sub_f32_e32 v30, v30, v65
	v_add_f32_e32 v16, v104, v16
	v_exp_f32_e32 v107, v29
	v_sub_f32_e32 v31, v31, v65
	v_add_f32_e32 v16, v105, v16
	v_exp_f32_e32 v108, v30
	v_sub_f32_e32 v0, v0, v65
	v_add_f32_e32 v16, v58, v16
	v_exp_f32_e32 v59, v31
	v_sub_f32_e32 v1, v1, v65
	v_add_f32_e32 v16, v106, v16
	v_exp_f32_e32 v109, v0
	v_sub_f32_e32 v2, v2, v65
	v_add_f32_e32 v16, v107, v16
	v_exp_f32_e32 v110, v1
	v_sub_f32_e32 v3, v3, v65
	v_add_f32_e32 v16, v108, v16
	v_exp_f32_e32 v111, v2
	v_sub_f32_e32 v4, v4, v65
	v_add_f32_e32 v16, v59, v16
	v_exp_f32_e32 v60, v3
	v_sub_f32_e32 v5, v5, v65
	v_add_f32_e32 v0, v109, v16
	v_exp_f32_e32 v112, v4
	v_sub_f32_e32 v6, v6, v65
	v_add_f32_e32 v0, v110, v0
	v_exp_f32_e32 v113, v5
	v_sub_f32_e32 v7, v7, v65
	v_add_f32_e32 v0, v111, v0
	v_exp_f32_e32 v114, v6
	v_sub_f32_e32 v8, v8, v65
	v_add_f32_e32 v0, v60, v0
	v_exp_f32_e32 v61, v7
	v_sub_f32_e32 v9, v9, v65
	v_add_f32_e32 v0, v112, v0
	v_exp_f32_e32 v115, v8
	v_sub_f32_e32 v10, v10, v65
	v_sub_f32_e32 v12, v12, v65
	v_sub_f32_e32 v13, v13, v65
	v_sub_f32_e32 v14, v14, v65
	v_sub_f32_e32 v15, v15, v65
	v_add_f32_e32 v0, v113, v0
	v_exp_f32_e32 v116, v9
	v_sub_f32_e32 v11, v11, v65
	v_add_f32_e32 v0, v114, v0
	v_exp_f32_e32 v117, v10
	v_exp_f32_e32 v118, v12
	v_exp_f32_e32 v119, v13
	v_exp_f32_e32 v120, v14
	v_exp_f32_e32 v63, v15
	ds_read_b64_tr_b16 v[12:13], v96 offset:9216
	ds_read_b64_tr_b16 v[14:15], v96 offset:10368
	ds_read_b64_tr_b16 v[18:19], v96 offset:10432
	ds_read_b64_tr_b16 v[16:17], v96 offset:9280
	ds_read_b64_tr_b16 v[20:21], v96 offset:11520
	ds_read_b64_tr_b16 v[22:23], v96 offset:12672
	ds_read_b64_tr_b16 v[26:27], v96 offset:12736
	ds_read_b64_tr_b16 v[24:25], v96 offset:11584
	v_add_f32_e32 v0, v61, v0
	v_exp_f32_e32 v62, v11
	v_add_f32_e32 v0, v115, v0
	v_add_f32_e32 v0, v116, v0
	v_add_f32_e32 v0, v117, v0
	v_exp_f32_e64 v48, -v65
	v_add_f32_e32 v0, v62, v0
	v_add_f32_e32 v0, v118, v0
	v_add_f32_e32 v0, v119, v0
	v_add_f32_e32 v0, v120, v0
	v_mul_f32_e32 v64, 0, v48
	v_add_f32_e32 v186, v63, v0
	v_pk_add_f32 v[48:49], v[64:65], v[186:187]
	v_cvt_pk_bf16_f32 v0, v97, v98
	v_cvt_pk_bf16_f32 v2, v100, v101
	v_cvt_pk_bf16_f32 v3, v102, v57
	v_cvt_pk_bf16_f32 v4, v103, v104
	v_cvt_pk_bf16_f32 v5, v105, v58
	v_cvt_pk_bf16_f32 v6, v106, v107
	v_cvt_pk_bf16_f32 v7, v108, v59
	v_cvt_pk_bf16_f32 v8, v109, v110
	v_cvt_pk_bf16_f32 v9, v111, v60
	v_cvt_pk_bf16_f32 v10, v112, v113
	v_cvt_pk_bf16_f32 v11, v114, v61
	v_cvt_pk_bf16_f32 v28, v115, v116
	v_cvt_pk_bf16_f32 v29, v117, v62
	v_cvt_pk_bf16_f32 v30, v118, v119
	v_cvt_pk_bf16_f32 v31, v120, v63
	v_cvt_pk_bf16_f32 v1, v99, v56
	s_setprio 1
	v_mov_b32_e32 v65, v64
	v_mov_b32_e32 v66, v64
	v_mov_b32_e32 v67, v64
	v_mov_b32_e32 v68, v64
	v_mov_b32_e32 v69, v64
	v_mov_b32_e32 v70, v64
	v_mov_b32_e32 v71, v64
	v_mov_b32_e32 v72, v64
	v_mov_b32_e32 v73, v64
	v_mov_b32_e32 v74, v64
	v_mov_b32_e32 v75, v64
	v_mov_b32_e32 v76, v64
	v_mov_b32_e32 v77, v64
	v_mov_b32_e32 v78, v64
	v_mov_b32_e32 v79, v64
	s_waitcnt lgkmcnt(6)
	s_nop 0
	v_mfma_f32_32x32x16_bf16 v[80:95], v[12:15], v[0:3], v[64:79]
	s_waitcnt lgkmcnt(4)
	v_mfma_f32_32x32x16_bf16 v[64:79], v[16:19], v[0:3], v[64:79]
	s_setprio 0
	ds_read_b64_tr_b16 v[0:1], v96 offset:13824
	ds_read_b64_tr_b16 v[2:3], v96 offset:14976
	ds_read_b64_tr_b16 v[14:15], v96 offset:15040
	ds_read_b64_tr_b16 v[12:13], v96 offset:13888
	s_setprio 1
	s_waitcnt lgkmcnt(6)
	v_mfma_f32_32x32x16_bf16 v[80:95], v[20:23], v[4:7], v[80:95]
	s_waitcnt lgkmcnt(4)
	v_mfma_f32_32x32x16_bf16 v[64:79], v[24:27], v[4:7], v[64:79]
	s_setprio 0
	ds_read_b64_tr_b16 v[4:5], v96 offset:16128
	ds_read_b64_tr_b16 v[6:7], v96 offset:17280
	ds_read_b64_tr_b16 v[18:19], v96 offset:17344
	ds_read_b64_tr_b16 v[16:17], v96 offset:16192
	s_setprio 1
	s_waitcnt lgkmcnt(6)
	v_mfma_f32_32x32x16_bf16 v[80:95], v[0:3], v[8:11], v[80:95]
	s_waitcnt lgkmcnt(4)
	v_mfma_f32_32x32x16_bf16 v[64:79], v[12:15], v[8:11], v[64:79]
	s_setprio 0
	s_setprio 1
	s_waitcnt lgkmcnt(2)
	v_mfma_f32_32x32x16_bf16 v[80:95], v[4:7], v[28:31], v[80:95]
	s_waitcnt lgkmcnt(0)
	v_mfma_f32_32x32x16_bf16 v[64:79], v[16:19], v[28:31], v[64:79]
	s_setprio 0
	s_barrier
; #define LAS __attribute__((address_space(3)))
; #define MFMA32(a, b, c) __builtin_amdgcn_mfma_f32_32x32x16_bf16((a), (b), (c), 0, 0, 0)
; #define SBAR() __builtin_amdgcn_sched_barrier(0)
; template <int KSTR> DI void qk64b(f32x16& s0, f32x16& s1, const lds8* kp, const bf16x8 (&q)[4], float bias) {
;   bf16x8 a[8];
; #pragma unroll
;   for (int ks = 0; ks < 4; ++ks) { a[2 * ks] = *(const LAS bf16x8*)(kp + ks * 32); a[2 * ks + 1] = *(const LAS bf16x8*)(kp + 32 * KSTR + ks * 32); }
; #pragma unroll
;   for (int i = 0; i < 16; ++i) { s0[i] = bias; s1[i] = bias; }
;   SBAR();
;   __builtin_amdgcn_s_setprio(1);
; #pragma unroll
;   for (int ks = 0; ks < 4; ++ks) { s0 = MFMA32(a[2 * ks], q[ks], s0); s1 = MFMA32(a[2 * ks + 1], q[ks], s1); }
;   __builtin_amdgcn_s_setprio(0);
;   SBAR();
; }
; template <int MODE, int SLOT> DI void ns_valu(volatile LAS int* jl, int t, int ntl, int qpos, int h, int blk, f32x16& s0, f32x16& s1, f32x16& du0, f32x16& du1, f32x16 (&O)[2], float& muse, float& l, bf16x8 (&P)[4], CmpCap& cap) {
;     if (t < ntl) {
;       const int j = __builtin_amdgcn_readfirstlane(jl[t]);
;       if (MODE == 0) {
;         const int lim = ((qpos - 31) >> 4) - 64 * j - 4 * h;
; #pragma unroll
;         for (int i = 0; i < 16; ++i) { const int ci = (i & 3) + 8 * (i >> 2); if (ci > lim) s0[i] = NEG; if (ci + 32 > lim) s1[i] = NEG; }
	ds_read_b128 v[122:125], v134 offset:18432
	ds_read_b128 v[126:129], v134 offset:18464
	ds_read_b128 v[130:133], v134 offset:23040
	ds_read_b128 v[138:141], v134 offset:23072
	ds_read_b128 v[142:145], v134 offset:18496
	ds_read_b128 v[146:149], v134 offset:18528
	ds_read_b128 v[150:153], v134 offset:23104
	ds_read_b128 v[154:157], v134 offset:23136
	v_xor_b32_e32 v0, 0x80000000, v49
	v_mov_b32_e32 v2, v0
	v_mov_b32_e32 v3, v0
	v_mov_b32_e32 v4, v0
	v_mov_b32_e32 v5, v0
	v_mov_b32_e32 v6, v0
	v_mov_b32_e32 v7, v0
	v_mov_b32_e32 v8, v0
	v_mov_b32_e32 v9, v0
	v_mov_b32_e32 v10, v0
	v_mov_b32_e32 v11, v0
	v_mov_b32_e32 v12, v0
	v_mov_b32_e32 v13, v0
	v_mov_b32_e32 v14, v0
	v_mov_b32_e32 v15, v0
	v_mov_b32_e32 v1, v0
	s_setprio 1
	s_waitcnt lgkmcnt(7)
	v_mfma_f32_32x32x16_bf16 v[16:31], v[122:125], v[44:47], v[0:15]
	s_waitcnt lgkmcnt(5)
	v_mfma_f32_32x32x16_bf16 v[0:15], v[130:133], v[44:47], v[0:15]
	v_mfma_f32_32x32x16_bf16 v[16:31], v[126:129], v[36:39], v[16:31]
	s_waitcnt lgkmcnt(4)
	v_mfma_f32_32x32x16_bf16 v[0:15], v[138:141], v[36:39], v[0:15]
	s_waitcnt lgkmcnt(3)
	v_mfma_f32_32x32x16_bf16 v[16:31], v[142:145], v[40:43], v[16:31]
	s_waitcnt lgkmcnt(1)
	v_mfma_f32_32x32x16_bf16 v[0:15], v[150:153], v[40:43], v[0:15]
	v_mfma_f32_32x32x16_bf16 v[16:31], v[146:149], v[32:35], v[16:31]
	s_waitcnt lgkmcnt(0)
	v_mfma_f32_32x32x16_bf16 v[0:15], v[154:157], v[32:35], v[0:15]
	s_setprio 0
	ds_read_b32 v50, v50
	s_waitcnt lgkmcnt(0)
	v_readfirstlane_b32 s6, v50
	s_nop 1
	v_lshl_or_b32 v50, s6, 6, v214
	v_sub_u32_e32 v121, v121, v50
	v_cmp_gt_i32_e64 s[64:65], 26, v121
	v_cmp_gt_i32_e64 s[68:69], 27, v121
	v_cmp_gt_i32_e64 s[60:61], 25, v121
	s_and_b64 s[64:65], s[68:69], s[64:65]
	v_cmp_gt_i32_e64 s[56:57], 24, v121
	s_and_b64 s[60:61], s[64:65], s[60:61]
	v_cmp_gt_i32_e64 s[52:53], 19, v121
	s_and_b64 s[56:57], s[60:61], s[56:57]
	v_cmp_gt_i32_e64 s[48:49], 18, v121
	s_and_b64 s[52:53], s[56:57], s[52:53]
	v_cmp_gt_i32_e64 s[44:45], 17, v121
	s_and_b64 s[48:49], s[52:53], s[48:49]
	v_cmp_gt_i32_e64 s[40:41], 16, v121
	s_and_b64 s[44:45], s[48:49], s[44:45]
	v_cmp_gt_i32_e64 s[36:37], 11, v121
	s_and_b64 s[40:41], s[44:45], s[40:41]
	v_cmp_gt_i32_e64 s[30:31], 10, v121
	s_and_b64 s[36:37], s[40:41], s[36:37]
	v_cmp_gt_i32_e64 s[26:27], 9, v121
	s_and_b64 s[30:31], s[36:37], s[30:31]
	v_cmp_gt_i32_e64 s[22:23], 8, v121
	s_and_b64 s[26:27], s[30:31], s[26:27]
	v_cmp_gt_i32_e64 s[20:21], 3, v121
	s_and_b64 s[22:23], s[26:27], s[22:23]
	v_cmp_gt_i32_e64 s[18:19], 2, v121
	s_and_b64 s[20:21], s[22:23], s[20:21]
	v_cmp_gt_i32_e64 s[16:17], 1, v121
	s_and_b64 s[18:19], s[20:21], s[18:19]
	v_cmp_gt_i32_e64 s[14:15], 0, v121
	s_and_b64 s[16:17], s[18:19], s[16:17]
	s_and_b64 s[14:15], s[16:17], s[14:15]
	v_cmp_gt_i32_e64 s[66:67], 58, v121
	v_cndmask_b32_e64 v50, v16, v207, s[14:15]
	v_cmp_gt_i32_e64 s[14:15], 59, v121
	v_cmp_gt_i32_e64 s[62:63], 57, v121
	v_cmp_gt_i32_e64 s[58:59], 56, v121
	v_cndmask_b32_e64 v15, v15, v207, s[14:15]
	s_and_b64 s[14:15], s[14:15], s[66:67]
	v_cndmask_b32_e64 v14, v14, v207, s[14:15]
	s_and_b64 s[14:15], s[14:15], s[62:63]
	v_cmp_gt_i32_e64 s[54:55], 51, v121
	v_cndmask_b32_e64 v13, v13, v207, s[14:15]
	s_and_b64 s[14:15], s[14:15], s[58:59]
	v_cmp_gt_i32_e64 s[50:51], 50, v121
	v_cndmask_b32_e64 v12, v12, v207, s[14:15]
	s_and_b64 s[14:15], s[14:15], s[54:55]
	v_cmp_gt_i32_e64 s[46:47], 49, v121
	v_cndmask_b32_e64 v11, v11, v207, s[14:15]
	s_and_b64 s[14:15], s[14:15], s[50:51]
	v_cmp_gt_i32_e64 s[42:43], 48, v121
	v_cndmask_b32_e64 v10, v10, v207, s[14:15]
	s_and_b64 s[14:15], s[14:15], s[46:47]
	v_cmp_gt_i32_e64 s[38:39], 43, v121
	v_cndmask_b32_e64 v9, v9, v207, s[14:15]
	s_and_b64 s[14:15], s[14:15], s[42:43]
	v_cmp_gt_i32_e64 s[34:35], 42, v121
	v_cndmask_b32_e64 v8, v8, v207, s[14:15]
	s_and_b64 s[14:15], s[14:15], s[38:39]
	v_cmp_gt_i32_e64 s[28:29], 41, v121
	v_cndmask_b32_e64 v7, v7, v207, s[14:15]
	s_and_b64 s[14:15], s[14:15], s[34:35]
	v_cmp_gt_i32_e64 s[24:25], 40, v121
	v_cndmask_b32_e64 v6, v6, v207, s[14:15]
	s_and_b64 s[14:15], s[14:15], s[28:29]
	v_cmp_gt_i32_e64 s[12:13], 35, v121
	v_cndmask_b32_e64 v5, v5, v207, s[14:15]
	s_and_b64 s[14:15], s[14:15], s[24:25]
	v_cmp_gt_i32_e64 s[10:11], 34, v121
	s_and_b64 s[12:13], s[14:15], s[12:13]
	v_cmp_gt_i32_e64 s[8:9], 33, v121
	s_and_b64 s[10:11], s[12:13], s[10:11]
	v_cmp_gt_i32_e32 vcc, 32, v121
	s_and_b64 s[8:9], s[10:11], s[8:9]
	v_cndmask_b32_e64 v51, v17, v207, s[16:17]
	s_and_b64 vcc, s[8:9], vcc
	v_cndmask_b32_e64 v17, v1, v207, s[8:9]
	v_cndmask_b32_e32 v16, v0, v207, vcc
	v_max_f32_e32 v0, v51, v51
	v_max_f32_e32 v1, v50, v50
	v_cndmask_b32_e64 v19, v19, v207, s[20:21]
	v_cndmask_b32_e64 v18, v18, v207, s[18:19]
	v_cndmask_b32_e64 v2, v2, v207, s[10:11]
	v_max_f32_e32 v0, v1, v0
	v_cndmask_b32_e64 v23, v23, v207, s[36:37]
	v_cndmask_b32_e64 v22, v22, v207, s[30:31]
	v_cndmask_b32_e64 v20, v20, v207, s[22:23]
	v_cndmask_b32_e64 v3, v3, v207, s[12:13]
	v_max3_f32 v1, v18, v19, v17
	v_max3_f32 v0, v0, v16, v2
	v_cndmask_b32_e64 v21, v21, v207, s[26:27]
	v_cndmask_b32_e64 v4, v4, v207, s[14:15]
	v_max3_f32 v0, v0, v3, v20
	v_max3_f32 v1, v1, v22, v23
	v_cndmask_b32_e64 v27, v27, v207, s[52:53]
	v_cndmask_b32_e64 v26, v26, v207, s[48:49]
	v_cndmask_b32_e64 v24, v24, v207, s[40:41]
	v_max3_f32 v0, v0, v21, v4
	v_max3_f32 v1, v1, v6, v7
	v_cndmask_b32_e64 v25, v25, v207, s[44:45]
	v_max3_f32 v0, v0, v5, v24
	v_max3_f32 v1, v1, v26, v27
	v_cndmask_b32_e64 v31, v31, v207, s[68:69]
	v_cndmask_b32_e64 v30, v30, v207, s[64:65]
	v_cndmask_b32_e64 v28, v28, v207, s[56:57]
	v_max3_f32 v0, v0, v25, v8
	v_max3_f32 v1, v1, v10, v11
	v_cndmask_b32_e64 v29, v29, v207, s[60:61]
	v_max3_f32 v0, v0, v9, v28
	v_max3_f32 v1, v1, v30, v31
	v_max3_f32 v0, v0, v29, v12
	v_max3_f32 v1, v1, v14, v15
	v_max3_f32 v0, v0, v13, v1
	ds_bpermute_b32 v1, v193, v0
	s_waitcnt lgkmcnt(0)
	v_max_f32_e32 v1, v1, v1
	v_max_f32_e32 v0, v0, v1
	v_cmp_lt_f32_e32 vcc, s7, v0
	s_cbranch_vccz .LBB0_902
; template <int NDVB, bool HAS_NEXT> DI void softmax_def(f32x16& sa0, f32x16& sa1, f32x16& sb0, f32x16& sb1, f32x16 (&O)[NDVB], float& muse, float& l, bool first, bf16x8 (&P)[4], bool check = true) {
;   float mx = 0.f;
;   if (check) mx = rowmax32(sa0, sa1);
;   if (check && (first || __any(mx > 8.f))) {
;     float dl = first ? mx : fmaxf(mx, 0.f);
;     if (mx < -1e29f) dl = 0.f;
;     const float alpha = __builtin_amdgcn_exp2f(-dl);
;     muse += dl; l *= alpha;
; #pragma unroll
;     for (int i = 0; i < 16; ++i) { sa0[i] -= dl; sa1[i] -= dl; }
;     if (HAS_NEXT) {
; #pragma unroll
;       for (int i = 0; i < 16; ++i) { sb0[i] -= dl; sb1[i] -= dl; }
;     }
; #pragma unroll
;     for (int d = 0; d < NDVB; ++d)
; #pragma unroll
;       for (int i = 0; i < 16; ++i) O[d][i] *= alpha;
;   }
	v_max_f32_e32 v1, v0, v0
	v_max_f32_e32 v1, 0, v1
	v_cmp_ngt_f32_e32 vcc, s85, v0
	s_nop 1
	v_cndmask_b32_e32 v121, 0, v1, vcc
	v_exp_f32_e64 v122, -v121
	v_pk_add_f32 v[0:1], v[48:49], v[120:121]
	v_pk_mul_f32 v[78:79], v[78:79], v[122:123] op_sel_hi:[1,0]
	v_mov_b32_e32 v0, v121
	v_pk_add_f32 v[50:51], v[50:51], v[0:1] op_sel_hi:[1,0] neg_lo:[0,1] neg_hi:[0,1]
	v_pk_add_f32 v[16:17], v[16:17], v[0:1] op_sel_hi:[1,0] neg_lo:[0,1] neg_hi:[0,1]
	v_pk_add_f32 v[18:19], v[18:19], v[0:1] op_sel_hi:[1,0] neg_lo:[0,1] neg_hi:[0,1]
	v_pk_add_f32 v[2:3], v[2:3], v[0:1] op_sel_hi:[1,0] neg_lo:[0,1] neg_hi:[0,1]
	v_pk_add_f32 v[20:21], v[20:21], v[0:1] op_sel_hi:[1,0] neg_lo:[0,1] neg_hi:[0,1]
	v_pk_add_f32 v[4:5], v[4:5], v[0:1] op_sel_hi:[1,0] neg_lo:[0,1] neg_hi:[0,1]
	v_pk_add_f32 v[22:23], v[22:23], v[0:1] op_sel_hi:[1,0] neg_lo:[0,1] neg_hi:[0,1]
	v_pk_add_f32 v[6:7], v[6:7], v[0:1] op_sel_hi:[1,0] neg_lo:[0,1] neg_hi:[0,1]
	v_pk_add_f32 v[24:25], v[24:25], v[0:1] op_sel_hi:[1,0] neg_lo:[0,1] neg_hi:[0,1]
	v_pk_add_f32 v[8:9], v[8:9], v[0:1] op_sel_hi:[1,0] neg_lo:[0,1] neg_hi:[0,1]
	v_pk_add_f32 v[26:27], v[26:27], v[0:1] op_sel_hi:[1,0] neg_lo:[0,1] neg_hi:[0,1]
	v_pk_add_f32 v[10:11], v[10:11], v[0:1] op_sel_hi:[1,0] neg_lo:[0,1] neg_hi:[0,1]
	v_pk_add_f32 v[28:29], v[28:29], v[0:1] op_sel_hi:[1,0] neg_lo:[0,1] neg_hi:[0,1]
	v_pk_add_f32 v[12:13], v[12:13], v[0:1] op_sel_hi:[1,0] neg_lo:[0,1] neg_hi:[0,1]
	v_pk_add_f32 v[30:31], v[30:31], v[0:1] op_sel_hi:[1,0] neg_lo:[0,1] neg_hi:[0,1]
	v_pk_add_f32 v[14:15], v[14:15], v[0:1] op_sel_hi:[1,0] neg_lo:[0,1] neg_hi:[0,1]
	v_pk_mul_f32 v[76:77], v[76:77], v[122:123] op_sel_hi:[1,0]
	v_pk_mul_f32 v[74:75], v[74:75], v[122:123] op_sel_hi:[1,0]
	v_pk_mul_f32 v[72:73], v[72:73], v[122:123] op_sel_hi:[1,0]
	v_pk_mul_f32 v[70:71], v[70:71], v[122:123] op_sel_hi:[1,0]
	v_pk_mul_f32 v[68:69], v[68:69], v[122:123] op_sel_hi:[1,0]
	v_pk_mul_f32 v[66:67], v[66:67], v[122:123] op_sel_hi:[1,0]
	v_pk_mul_f32 v[64:65], v[64:65], v[122:123] op_sel_hi:[1,0]
	v_pk_mul_f32 v[94:95], v[94:95], v[122:123] op_sel_hi:[1,0]
	v_pk_mul_f32 v[92:93], v[92:93], v[122:123] op_sel_hi:[1,0]
	v_pk_mul_f32 v[90:91], v[90:91], v[122:123] op_sel_hi:[1,0]
	v_pk_mul_f32 v[88:89], v[88:89], v[122:123] op_sel_hi:[1,0]
	v_pk_mul_f32 v[86:87], v[86:87], v[122:123] op_sel_hi:[1,0]
	v_pk_mul_f32 v[84:85], v[84:85], v[122:123] op_sel_hi:[1,0]
	v_pk_mul_f32 v[82:83], v[82:83], v[122:123] op_sel_hi:[1,0]
	v_pk_mul_f32 v[80:81], v[80:81], v[122:123] op_sel_hi:[1,0]
	v_mul_f32_e32 v48, v48, v122
	s_branch .LBB0_903

; #define NS_GLOAD(k_, KR, VR) do { const int jj = __builtin_amdgcn_readfirstlane(jl[(k_)]); KR = *(const u32x4*)(kg + (size_t)(64 * jj + sr) * pitch + sc * 8); VR = *(const u32x4*)(vg + (size_t)(64 * jj + sr) * pitch + sc * 8); } while (0)
; #define NS_LSTORE(st_, KR, VR) do { lds8* b = lds + (st_) * NS_STAGE; *(LAS u32x4*)(b + sr * NS_STR + sc * 16) = KR; *(LAS u32x4*)(b + 64 * NS_STR + sr * NS_STR + sc * 16) = VR; } while (0)
; template <int MODE>
; DI void nsa_branch(lds8* lds, const bf16_t* kg, const bf16_t* vg, int pitch, unsigned tiles, const bf16x8 (&q)[4], int qpos, unsigned mybits, int blk,
;                    f32x16 (&O)[2], float& muse, float& l, int tid, int lane, int grp, CmpCap& cap) {
;     ...
;   NS_GLOAD(0, kra, vra); NS_LSTORE(0, kra, vra);
;   if (ntl > 1) { NS_GLOAD(1, kra, vra); NS_LSTORE(1, kra, vra); }
;   __syncthreads();
.LBB0_932:
	s_or_b64 exec, exec, s[10:11]
	s_lshl_b32 s10, s71, 20
	v_readlane_b32 s1, v254, 53
	s_add_u32 s11, s1, s10
	v_readlane_b32 s1, v254, 54
	v_mov_b32_e32 v48, s0
	s_addc_u32 s12, s1, 0
	s_lshl_b32 s13, s70, 7
	s_waitcnt lgkmcnt(0)
	s_barrier
	ds_read_b32 v48, v48
	s_add_u32 s78, s11, s13
	s_addc_u32 s79, s12, 0
	v_readlane_b32 s1, v254, 59
	s_add_u32 s10, s1, s10
	v_readlane_b32 s1, v254, 60
	s_addc_u32 s11, s1, 0
	s_add_u32 s80, s10, s13
	s_addc_u32 s81, s11, 0
	v_readlane_b32 s1, v255, 9
	v_lshlrev_b32_e32 v186, 1, v54
	s_bcnt1_i32_b32 s88, s6
	v_mov_b32_e32 v112, s1
	ds_read_b32 v112, v112
	s_waitcnt lgkmcnt(0)
	v_readfirstlane_b32 s10, v48
	v_readfirstlane_b32 s11, v112
	s_nop 1
	v_lshl_add_u32 v48, s10, 6, v212
	v_lshl_add_u32 v112, s11, 6, v212
	v_ashrrev_i32_e32 v49, 31, v48
	v_lshlrev_b64 v[48:49], 9, v[48:49]
	v_lshl_add_u64 v[50:51], s[78:79], 0, v[48:49]
	v_lshl_add_u64 v[50:51], v[50:51], 0, v[186:187]
	v_lshl_add_u64 v[48:49], s[80:81], 0, v[48:49]
	v_lshl_add_u64 v[48:49], v[48:49], 0, v[186:187]
	global_load_dwordx4 v[128:131], v[50:51], off
	global_load_dwordx4 v[132:135], v[48:49], off
	s_cmp_lt_u32 s88, 2
	s_cbranch_scc1 .Lslc_pro_one
	v_ashrrev_i32_e32 v113, 31, v112
	v_lshlrev_b64 v[112:113], 9, v[112:113]
	v_lshl_add_u64 v[50:51], s[78:79], 0, v[112:113]
	v_lshl_add_u64 v[48:49], s[80:81], 0, v[112:113]
	v_lshl_add_u64 v[50:51], v[50:51], 0, v[186:187]
	v_lshl_add_u64 v[48:49], v[48:49], 0, v[186:187]
	global_load_dwordx4 v[112:115], v[50:51], off
	global_load_dwordx4 v[116:119], v[48:49], off
	s_waitcnt vmcnt(3)
	ds_write_b128 v215, v[128:131]
	s_waitcnt vmcnt(2)
	ds_write_b128 v215, v[132:135] offset:9216
	s_waitcnt vmcnt(1)
	ds_write_b128 v215, v[112:115] offset:18432
	s_waitcnt vmcnt(0)
	ds_write_b128 v215, v[116:119] offset:27648
	s_branch .LBB0_934
.Lslc_pro_one:
	s_waitcnt vmcnt(1)
	ds_write_b128 v215, v[128:131]
	s_waitcnt vmcnt(0)
	ds_write_b128 v215, v[132:135] offset:9216

; #define NS_GLOAD(k_, KR, VR) do { const int jj = __builtin_amdgcn_readfirstlane(jl[(k_)]); KR = *(const u32x4*)(kg + (size_t)(64 * jj + sr) * pitch + sc * 8); VR = *(const u32x4*)(vg + (size_t)(64 * jj + sr) * pitch + sc * 8); } while (0)
; #define NS_LSTORE(st_, KR, VR) do { lds8* b = lds + (st_) * NS_STAGE; *(LAS u32x4*)(b + sr * NS_STR + sc * 16) = KR; *(LAS u32x4*)(b + 64 * NS_STR + sr * NS_STR + sc * 16) = VR; } while (0)
; template <int MODE>
; DI void nsa_branch(lds8* lds, const bf16_t* kg, const bf16_t* vg, int pitch, unsigned tiles, const bf16x8 (&q)[4], int qpos, unsigned mybits, int blk,
;                    f32x16 (&O)[2], float& muse, float& l, int tid, int lane, int grp, CmpCap& cap) {
;     ...
;   NS_GLOAD(0, kra, vra); NS_LSTORE(0, kra, vra);
;   if (ntl > 1) { NS_GLOAD(1, kra, vra); NS_LSTORE(1, kra, vra); }
;   __syncthreads();
.LBB0_975:
	s_or_b64 exec, exec, s[10:11]
	v_mov_b32_e32 v32, s0
	v_readlane_b32 s1, v255, 9
	s_waitcnt lgkmcnt(0)
	s_barrier
	ds_read_b32 v32, v32
	v_mov_b32_e32 v36, s1
	ds_read_b32 v36, v36
	s_waitcnt lgkmcnt(0)
	v_readfirstlane_b32 s3, v32
	v_readfirstlane_b32 s8, v36
	s_nop 1
	v_lshl_add_u32 v32, s3, 6, v212
	v_lshl_add_u32 v36, s8, 6, v212
	v_ashrrev_i32_e32 v33, 31, v32
	v_lshlrev_b64 v[32:33], 9, v[32:33]
	v_lshl_add_u64 v[34:35], s[78:79], 0, v[32:33]
	v_lshl_add_u64 v[32:33], s[80:81], 0, v[32:33]
	v_lshl_add_u64 v[34:35], v[34:35], 0, v[186:187]
	v_lshl_add_u64 v[32:33], v[32:33], 0, v[186:187]
	global_load_dwordx4 v[176:179], v[34:35], off offset:256
	global_load_dwordx4 v[180:183], v[32:33], off offset:256
	s_bcnt1_i32_b32 s3, s6
	s_cmp_lt_u32 s3, 2
	s_cbranch_scc1 .Lwin_pro_one
	v_ashrrev_i32_e32 v37, 31, v36
	v_lshlrev_b64 v[36:37], 9, v[36:37]
	v_lshl_add_u64 v[38:39], s[78:79], 0, v[36:37]
	v_lshl_add_u64 v[36:37], s[80:81], 0, v[36:37]
	v_lshl_add_u64 v[38:39], v[38:39], 0, v[186:187]
	v_lshl_add_u64 v[36:37], v[36:37], 0, v[186:187]
	global_load_dwordx4 v[40:43], v[38:39], off offset:256
	global_load_dwordx4 v[44:47], v[36:37], off offset:256
	s_waitcnt vmcnt(3)
	ds_write_b128 v215, v[176:179]
	s_waitcnt vmcnt(2)
	ds_write_b128 v215, v[180:183] offset:9216
	s_waitcnt vmcnt(1)
	ds_write_b128 v215, v[40:43] offset:18432
	s_waitcnt vmcnt(0)
	ds_write_b128 v215, v[44:47] offset:27648
	s_branch .LBB0_977
.Lwin_pro_one:
	s_waitcnt vmcnt(1)
	ds_write_b128 v215, v[176:179]
	s_waitcnt vmcnt(0)
	ds_write_b128 v215, v[180:183] offset:9216

; #define GSYNC() do { XcdBarrier b_; b_.bar = (unsigned*)(p.ws + OFF_BAR); b_.x = xb_xcc_id(); b_.st = (volatile LAS unsigned*)(lds + 131072 + 256); xcd_barrier(b_); } while (0)
; __global__ void __launch_bounds__(512, 2) fwd_mega(Params p) {
;     ...
;   for (int ck = 0; ck < NCHUNK; ++ck) {
;     const int row_off = ck * MC;
;     ...
;     { Gemm g{XB + (size_t)row_off * DM, (const bf16_t*)(ws + OFF_WIN), MC, NIN, DM}; StaticOrder S; S.init(MC, NIN, G, bid);
;     ...
;     GSYNC();
;   }
.Lskip_gsync_ck0:
	s_mov_b32 s42, 1
	s_mov_b64 s[16:17], 0
	s_waitcnt lgkmcnt(0)
	s_barrier
	s_branch .LBB0_615

; __device__ __forceinline__ unsigned xb_add(unsigned* p, unsigned v) { return __hip_atomic_fetch_add(p, v, __ATOMIC_RELAXED, __HIP_MEMORY_SCOPE_AGENT); }
; #define GSYNC() do { XcdBarrier b_; b_.bar = (unsigned*)(p.ws + OFF_BAR); b_.x = xb_xcc_id(); b_.st = (volatile LAS unsigned*)(lds + 131072 + 256); xcd_barrier(b_); } while (0)
; __device__ __forceinline__ void xcd_barrier(const XcdBarrier& b) {
;     asm volatile("s_waitcnt vmcnt(0)" ::: "memory");
;     __syncthreads();
;     if (threadIdx.x == 0) {
;         unsigned* bar = b.bar;
;         __builtin_amdgcn_s_waitcnt(0);
;         unsigned nloc = b.st[0], nx = b.st[1];
;         if (nloc == 0u) { xcd_barrier_complete(bar, b.x, nloc, nx); b.st[0] = nloc; b.st[1] = nx; }
;         const unsigned old = xb_add(&bar[XB_XSUB(b.x)], 1u);
; __global__ void __launch_bounds__(512, 2) fwd_mega(Params p) {
;     ...
;     GSYNC();
.LBB0_1193:
	v_readlane_b32 s0, v255, 33
	v_readlane_b32 s1, v255, 34
	s_nop 3
	s_and_b64 vcc, exec, s[0:1]
	s_cbranch_vccz .Lskip_gsync_ck0
	s_getreg_b32 s0, hwreg(HW_REG_XCC_ID, 0, 4)
	s_waitcnt vmcnt(0)
	s_waitcnt lgkmcnt(0)
	s_barrier
	s_and_saveexec_b64 s[8:9], s[62:63]
	s_cbranch_execz .LBB0_614
	v_readlane_b32 s1, v255, 3
	s_waitcnt vmcnt(0) expcnt(0) lgkmcnt(0)
	s_and_b32 s0, s0, 15
	v_mov_b32_e32 v0, s1
	ds_read_b32 v2, v0
	v_readlane_b32 s1, v255, 4
	s_waitcnt lgkmcnt(0)
	v_cmp_ne_u32_e32 vcc, 0, v2
	v_mov_b32_e32 v0, s1
	ds_read_b32 v0, v0
	s_cbranch_vccnz .LBB0_1209
	s_mov_b32 s1, 1
	s_branch .LBB0_1197
